# stack v68 + FFN-up epilogue: follow-up store addresses = first address + SGPR-pair row constant (one 64-bit add) instead of a 64-bit multiply-add chain per store
# speedup vs baseline: 1.0060x; 1.0060x over previous
; #define PG8_STAGE(bufoff, gbase, voff) do { _Pragma("unroll") for (int _i = 0; _i < 2; ++_i) \
;         __builtin_amdgcn_global_load_lds((const unsigned*)((const char*)(gbase) + (voff)[_i]), (LAS unsigned*)(lds + (bufoff) + ldsw + _i * 8192), 16, 0, 0); } while (0)
; #define PG8_LDA(dst, b, h) do { _Pragma("unroll") for (int m = 0; m < 4; ++m) _Pragma("unroll") for (int k = 0; k < 2; ++k) dst[m][k] = *(const LAS bf16x8*)(lds + PG8_SA(b, h) + aoff + m * 2048 + k * 1024); } while (0)
; #define PG8_LDB(dst, b, h) do { _Pragma("unroll") for (int n = 0; n < 2; ++n) _Pragma("unroll") for (int k = 0; k < 2; ++k) dst[n][k] = *(const LAS bf16x8*)(lds + PG8_SB(b, h) + boff + n * 2048 + k * 1024); } while (0)
; #define PG8_WAIT_V(n) asm volatile("s_waitcnt vmcnt(" #n ")" ::: "memory")
; #define PG8_WAIT_L(n) asm volatile("s_waitcnt lgkmcnt(" #n ")" ::: "memory")
; template <class Epi>
; __device__ __forceinline__ void gemm_phase(LAS unsigned char* lds, const Gemm g, const int G, const int cidx, const Epi& E) {
;     ...
;         for (int t = 0; t < nt; t += 2) {
;             const bool last = (t == nt - 2);
;             const char* a1 = cA + (size_t)(t + 1) * kstep;
;             const char* a2 = last ? nA : cA + (size_t)(t + 2) * kstep; const char* b2 = last ? nB : cB + (size_t)(t + 2) * kstep;
;             const char* a3 = a2 + kstep; const char* b3 = b2 + kstep;
;             PG8_LDB(B0, 0, 0); PG8_LDB(B1, 0, 1); PG8_SCHED; PG8_LDA(At, 0, 0); PG8_STAGE(PG8_SA(1, 1), a1 + hstep, voffA);
;             PG8_WAIT_V(8); PG8_WAIT_L(0); PG8_BAR; PG8_MMA(0, 0, At, B0); PG8_MMA(0, 1, At, B1); PG8_BAR; PG8_SCHED;
;             PG8_LDA(At, 0, 1); PG8_STAGE(PG8_SB(0, 0), b2, voffB); PG8_STAGE(PG8_SB(0, 1), b2 + hstep, voffB); PG8_STAGE(PG8_SA(0, 0), a2, voffA);
;             PG8_WAIT_V(8); PG8_WAIT_L(0); PG8_BAR; PG8_MMA(1, 0, At, B0); PG8_MMA(1, 1, At, B1); PG8_BAR; PG8_SCHED;
;             PG8_LDB(B0, 1, 0); PG8_LDB(B1, 1, 1); PG8_SCHED; PG8_LDA(At, 1, 0); PG8_STAGE(PG8_SA(0, 1), a2 + hstep, voffA);
;             PG8_WAIT_V(8); PG8_WAIT_L(0); PG8_BAR; PG8_MMA(0, 0, At, B0); PG8_MMA(0, 1, At, B1); PG8_BAR; PG8_SCHED;
;             PG8_LDA(At, 1, 1); PG8_STAGE(PG8_SB(1, 0), b3, voffB); PG8_STAGE(PG8_SB(1, 1), b3 + hstep, voffB); PG8_STAGE(PG8_SA(1, 0), a3, voffA);
;             PG8_WAIT_V(8); PG8_WAIT_L(0); PG8_BAR; PG8_MMA(1, 0, At, B0); PG8_MMA(1, 1, At, B1); PG8_BAR; PG8_SCHED;
.LBB0_82:
	s_add_u32 s26, s24, 0xfffc0080
	s_addc_u32 s27, s25, -1
	s_add_i32 s43, 0, 0x10000
	s_cmp_eq_u32 s45, 12
	s_cselect_b32 s29, s13, s27
	s_cselect_b32 s28, s17, s26
	s_cselect_b32 s27, s9, s44
	s_cselect_b32 s26, s22, s33
	s_add_i32 s68, 0, 0x14000
	v_add_u32_e32 v162, s43, v145
	v_add_u32_e32 v178, s68, v145
	ds_read_b128 v[132:135], v162
	ds_read_b128 v[140:143], v162 offset:1024
	ds_read_b128 v[156:159], v162 offset:2048
	ds_read_b128 v[162:165], v162 offset:3072
	ds_read_b128 v[166:169], v178
	ds_read_b128 v[170:173], v178 offset:1024
	ds_read_b128 v[174:177], v178 offset:2048
	ds_read_b128 v[178:181], v178 offset:3072
	v_lshl_add_u64 v[226:227], s[24:25], 0, v[154:155]
	s_add_i32 m0, s21, 0xc000
	ds_read_b128 v[182:185], v161
	ds_read_b128 v[186:189], v161 offset:1024
	ds_read_b128 v[190:193], v161 offset:2048
	ds_read_b128 v[194:197], v161 offset:3072
	ds_read_b128 v[198:201], v161 offset:4096
	ds_read_b128 v[214:217], v161 offset:5120
	ds_read_b128 v[218:221], v161 offset:6144
	ds_read_b128 v[222:225], v161 offset:7168
	global_load_lds_dwordx4 v[226:227], off
	v_lshl_add_u64 v[226:227], s[24:25], 0, v[152:153]
	s_add_i32 m0, s21, 0xe000
	s_nop 0
	global_load_lds_dwordx4 v[226:227], off
	s_waitcnt vmcnt(8)
	s_waitcnt lgkmcnt(0)
	s_barrier
	s_setprio 1
	s_waitcnt lgkmcnt(0)
	v_mfma_f32_16x16x32_bf16 v[128:131], v[132:135], v[182:185], v[128:131]
	v_mfma_f32_16x16x32_bf16 v[120:123], v[156:159], v[182:185], v[120:123]
	v_mfma_f32_16x16x32_bf16 v[112:115], v[132:135], v[190:193], v[112:115]
	v_mfma_f32_16x16x32_bf16 v[104:107], v[156:159], v[190:193], v[104:107]
	v_mfma_f32_16x16x32_bf16 v[96:99], v[132:135], v[198:201], v[96:99]
	v_mfma_f32_16x16x32_bf16 v[88:91], v[156:159], v[198:201], v[88:91]
	v_mfma_f32_16x16x32_bf16 v[80:83], v[132:135], v[218:221], v[80:83]
	v_mfma_f32_16x16x32_bf16 v[72:75], v[156:159], v[218:221], v[72:75]
	v_mfma_f32_16x16x32_bf16 v[128:131], v[140:143], v[186:189], v[128:131]
	v_mfma_f32_16x16x32_bf16 v[120:123], v[162:165], v[186:189], v[120:123]
	v_mfma_f32_16x16x32_bf16 v[112:115], v[140:143], v[194:197], v[112:115]
	v_mfma_f32_16x16x32_bf16 v[104:107], v[162:165], v[194:197], v[104:107]
	v_mfma_f32_16x16x32_bf16 v[96:99], v[140:143], v[214:217], v[96:99]
	v_mfma_f32_16x16x32_bf16 v[88:91], v[162:165], v[214:217], v[88:91]
	v_mfma_f32_16x16x32_bf16 v[80:83], v[140:143], v[222:225], v[80:83]
	v_mfma_f32_16x16x32_bf16 v[72:75], v[162:165], v[222:225], v[72:75]
	s_setprio 0
	s_setprio 1
	v_mfma_f32_16x16x32_bf16 v[124:127], v[166:169], v[182:185], v[124:127]
	v_mfma_f32_16x16x32_bf16 v[116:119], v[174:177], v[182:185], v[116:119]
	v_mfma_f32_16x16x32_bf16 v[108:111], v[166:169], v[190:193], v[108:111]
	v_mfma_f32_16x16x32_bf16 v[100:103], v[174:177], v[190:193], v[100:103]
	v_mfma_f32_16x16x32_bf16 v[92:95], v[166:169], v[198:201], v[92:95]
	v_mfma_f32_16x16x32_bf16 v[84:87], v[174:177], v[198:201], v[84:87]
	v_mfma_f32_16x16x32_bf16 v[76:79], v[166:169], v[218:221], v[76:79]
	v_mfma_f32_16x16x32_bf16 v[68:71], v[174:177], v[218:221], v[68:71]
	v_mfma_f32_16x16x32_bf16 v[124:127], v[170:173], v[186:189], v[124:127]
	v_mfma_f32_16x16x32_bf16 v[116:119], v[178:181], v[186:189], v[116:119]
	v_mfma_f32_16x16x32_bf16 v[108:111], v[170:173], v[194:197], v[108:111]
	v_mfma_f32_16x16x32_bf16 v[100:103], v[178:181], v[194:197], v[100:103]
	v_mfma_f32_16x16x32_bf16 v[92:95], v[170:173], v[214:217], v[92:95]
	v_mfma_f32_16x16x32_bf16 v[84:87], v[178:181], v[214:217], v[84:87]
	v_mfma_f32_16x16x32_bf16 v[76:79], v[170:173], v[222:225], v[76:79]
	v_mfma_f32_16x16x32_bf16 v[68:71], v[178:181], v[222:225], v[68:71]
	s_setprio 0
	s_barrier
	s_add_i32 s43, s43, s36
	v_lshl_add_u64 v[226:227], s[26:27], 0, v[148:149]
	s_mov_b32 m0, s43
	ds_read_b128 v[182:185], v161 offset:16384
	ds_read_b128 v[186:189], v161 offset:17408
	ds_read_b128 v[190:193], v161 offset:18432
	ds_read_b128 v[194:197], v161 offset:19456
	ds_read_b128 v[198:201], v161 offset:20480
	ds_read_b128 v[214:217], v161 offset:21504
	ds_read_b128 v[218:221], v161 offset:22528
	ds_read_b128 v[222:225], v161 offset:23552
	global_load_lds_dwordx4 v[226:227], off
	s_add_i32 m0, s43, 0x2000
	s_add_u32 s76, s26, 0x40000
	v_lshl_add_u64 v[228:229], s[26:27], 0, v[0:1]
	s_addc_u32 s77, s27, 0
	s_add_i32 s43, s68, s36
	global_load_lds_dwordx4 v[228:229], off
	v_lshl_add_u64 v[230:231], s[76:77], 0, v[148:149]
	s_mov_b32 m0, s43
	v_lshl_add_u64 v[232:233], s[28:29], 0, v[146:147]
	global_load_lds_dwordx4 v[230:231], off
	v_lshl_add_u64 v[230:231], s[76:77], 0, v[0:1]
	s_add_i32 m0, s43, 0x2000
	s_nop 0
	global_load_lds_dwordx4 v[230:231], off
	v_lshl_add_u64 v[230:231], s[28:29], 0, v[150:151]
	s_mov_b32 m0, s21
	s_nop 0
	global_load_lds_dwordx4 v[230:231], off
	s_mov_b32 m0, s38
	s_nop 0
	global_load_lds_dwordx4 v[232:233], off
	s_waitcnt vmcnt(8)
	s_waitcnt lgkmcnt(0)
	s_barrier
; #define PG8_STAGE(bufoff, gbase, voff) do { _Pragma("unroll") for (int _i = 0; _i < 2; ++_i) \
;         __builtin_amdgcn_global_load_lds((const unsigned*)((const char*)(gbase) + (voff)[_i]), (LAS unsigned*)(lds + (bufoff) + ldsw + _i * 8192), 16, 0, 0); } while (0)
; #define PG8_LDA(dst, b, h) do { _Pragma("unroll") for (int m = 0; m < 4; ++m) _Pragma("unroll") for (int k = 0; k < 2; ++k) dst[m][k] = *(const LAS bf16x8*)(lds + PG8_SA(b, h) + aoff + m * 2048 + k * 1024); } while (0)
; #define PG8_LDB(dst, b, h) do { _Pragma("unroll") for (int n = 0; n < 2; ++n) _Pragma("unroll") for (int k = 0; k < 2; ++k) dst[n][k] = *(const LAS bf16x8*)(lds + PG8_SB(b, h) + boff + n * 2048 + k * 1024); } while (0)
; #define PG8_MMA(ai, bj, At, Bt) do { __builtin_amdgcn_s_setprio(1); _Pragma("unroll") for (int m = 0; m < 4; ++m) _Pragma("unroll") for (int n = 0; n < 2; ++n) _Pragma("unroll") for (int k = 0; k < 2; ++k) \
;         acc[ai][bj][m][n] = __builtin_amdgcn_mfma_f32_16x16x32_bf16(Bt[n][k], At[m][k], acc[ai][bj][m][n], 0, 0, 0); __builtin_amdgcn_s_setprio(0); } while (0)
; #define PG8_WAIT_V(n) asm volatile("s_waitcnt vmcnt(" #n ")" ::: "memory")
; #define PG8_WAIT_L(n) asm volatile("s_waitcnt lgkmcnt(" #n ")" ::: "memory")
; #define PG8_BAR __builtin_amdgcn_s_barrier()
; #define PG8_SCHED __builtin_amdgcn_sched_barrier(0)
; template <class Epi>
; __device__ __forceinline__ void gemm_phase(LAS unsigned char* lds, const Gemm g, const int G, const int cidx, const Epi& E) {
;     ...
;             PG8_WAIT_V(8); PG8_WAIT_L(0); PG8_BAR; PG8_MMA(1, 0, At, B0); PG8_MMA(1, 1, At, B1); PG8_BAR; PG8_SCHED;
;             PG8_LDB(B0, 1, 0); PG8_LDB(B1, 1, 1); PG8_SCHED; PG8_LDA(At, 1, 0); PG8_STAGE(PG8_SA(0, 1), a2 + hstep, voffA);
;             PG8_WAIT_V(8); PG8_WAIT_L(0); PG8_BAR; PG8_MMA(0, 0, At, B0); PG8_MMA(0, 1, At, B1); PG8_BAR; PG8_SCHED;
;             PG8_LDA(At, 1, 1); PG8_STAGE(PG8_SB(1, 0), b3, voffB); PG8_STAGE(PG8_SB(1, 1), b3 + hstep, voffB); PG8_STAGE(PG8_SA(1, 0), a3, voffA);
;             PG8_WAIT_V(8); PG8_WAIT_L(0); PG8_BAR; PG8_MMA(1, 0, At, B0); PG8_MMA(1, 1, At, B1); PG8_BAR; PG8_SCHED;
	s_setprio 1
	s_waitcnt lgkmcnt(0)
	v_mfma_f32_16x16x32_bf16 v[64:67], v[132:135], v[182:185], v[64:67]
	v_mfma_f32_16x16x32_bf16 v[56:59], v[156:159], v[182:185], v[56:59]
	v_mfma_f32_16x16x32_bf16 v[48:51], v[132:135], v[190:193], v[48:51]
	v_mfma_f32_16x16x32_bf16 v[40:43], v[156:159], v[190:193], v[40:43]
	v_mfma_f32_16x16x32_bf16 v[32:35], v[132:135], v[198:201], v[32:35]
	v_mfma_f32_16x16x32_bf16 v[24:27], v[156:159], v[198:201], v[24:27]
	v_mfma_f32_16x16x32_bf16 v[16:19], v[132:135], v[218:221], v[16:19]
	v_mfma_f32_16x16x32_bf16 v[8:11], v[156:159], v[218:221], v[8:11]
	v_mfma_f32_16x16x32_bf16 v[64:67], v[140:143], v[186:189], v[64:67]
	v_mfma_f32_16x16x32_bf16 v[56:59], v[162:165], v[186:189], v[56:59]
	v_mfma_f32_16x16x32_bf16 v[48:51], v[140:143], v[194:197], v[48:51]
	v_mfma_f32_16x16x32_bf16 v[40:43], v[162:165], v[194:197], v[40:43]
	v_mfma_f32_16x16x32_bf16 v[32:35], v[140:143], v[214:217], v[32:35]
	v_mfma_f32_16x16x32_bf16 v[24:27], v[162:165], v[214:217], v[24:27]
	v_mfma_f32_16x16x32_bf16 v[16:19], v[140:143], v[222:225], v[16:19]
	v_mfma_f32_16x16x32_bf16 v[8:11], v[162:165], v[222:225], v[8:11]
	s_setprio 0
	s_setprio 1
	v_mfma_f32_16x16x32_bf16 v[60:63], v[166:169], v[182:185], v[60:63]
	v_mfma_f32_16x16x32_bf16 v[52:55], v[174:177], v[182:185], v[52:55]
	v_mfma_f32_16x16x32_bf16 v[44:47], v[166:169], v[190:193], v[44:47]
	v_mfma_f32_16x16x32_bf16 v[36:39], v[174:177], v[190:193], v[36:39]
	v_mfma_f32_16x16x32_bf16 v[28:31], v[166:169], v[198:201], v[28:31]
	v_mfma_f32_16x16x32_bf16 v[20:23], v[174:177], v[198:201], v[20:23]
	v_mfma_f32_16x16x32_bf16 v[12:15], v[166:169], v[218:221], v[12:15]
	v_mfma_f32_16x16x32_bf16 v[4:7], v[174:177], v[218:221], v[4:7]
	v_mfma_f32_16x16x32_bf16 v[60:63], v[170:173], v[186:189], v[60:63]
	v_mfma_f32_16x16x32_bf16 v[52:55], v[178:181], v[186:189], v[52:55]
	v_mfma_f32_16x16x32_bf16 v[44:47], v[170:173], v[194:197], v[44:47]
	v_mfma_f32_16x16x32_bf16 v[36:39], v[178:181], v[194:197], v[36:39]
	v_mfma_f32_16x16x32_bf16 v[28:31], v[170:173], v[214:217], v[28:31]
	v_mfma_f32_16x16x32_bf16 v[20:23], v[178:181], v[214:217], v[20:23]
	v_mfma_f32_16x16x32_bf16 v[12:15], v[170:173], v[222:225], v[12:15]
	v_mfma_f32_16x16x32_bf16 v[4:7], v[178:181], v[222:225], v[4:7]
	s_setprio 0
	s_barrier
	s_add_i32 s43, 0, 0x18000
	s_add_i32 s68, 0, 0x1c000
	v_add_u32_e32 v162, s43, v145
	v_add_u32_e32 v178, s68, v145
	ds_read_b128 v[132:135], v162
	ds_read_b128 v[140:143], v162 offset:1024
	ds_read_b128 v[156:159], v162 offset:2048
	ds_read_b128 v[162:165], v162 offset:3072
	ds_read_b128 v[166:169], v178
	ds_read_b128 v[170:173], v178 offset:1024
	ds_read_b128 v[174:177], v178 offset:2048
	ds_read_b128 v[178:181], v178 offset:3072
	s_add_u32 s28, s28, 0x40000
	s_addc_u32 s29, s29, 0
	s_mov_b32 m0, s39
	v_lshl_add_u64 v[234:235], s[28:29], 0, v[150:151]
	ds_read_b128 v[182:185], v161 offset:32768
	ds_read_b128 v[186:189], v161 offset:33792
	ds_read_b128 v[190:193], v161 offset:34816
	ds_read_b128 v[194:197], v161 offset:35840
	ds_read_b128 v[198:201], v161 offset:36864
	ds_read_b128 v[214:217], v161 offset:37888
	ds_read_b128 v[218:221], v161 offset:38912
	ds_read_b128 v[222:225], v161 offset:39936
	global_load_lds_dwordx4 v[234:235], off
	v_lshl_add_u64 v[234:235], s[28:29], 0, v[146:147]
	s_mov_b32 m0, s75
	s_nop 0
	global_load_lds_dwordx4 v[234:235], off
	s_waitcnt vmcnt(8)
	s_waitcnt lgkmcnt(0)
	s_barrier
	s_setprio 1
	s_waitcnt lgkmcnt(0)
	v_mfma_f32_16x16x32_bf16 v[128:131], v[132:135], v[182:185], v[128:131]
	v_mfma_f32_16x16x32_bf16 v[120:123], v[156:159], v[182:185], v[120:123]
	v_mfma_f32_16x16x32_bf16 v[112:115], v[132:135], v[190:193], v[112:115]
	v_mfma_f32_16x16x32_bf16 v[104:107], v[156:159], v[190:193], v[104:107]
	v_mfma_f32_16x16x32_bf16 v[96:99], v[132:135], v[198:201], v[96:99]
	v_mfma_f32_16x16x32_bf16 v[88:91], v[156:159], v[198:201], v[88:91]
	v_mfma_f32_16x16x32_bf16 v[80:83], v[132:135], v[218:221], v[80:83]
	v_mfma_f32_16x16x32_bf16 v[72:75], v[156:159], v[218:221], v[72:75]
	v_mfma_f32_16x16x32_bf16 v[128:131], v[140:143], v[186:189], v[128:131]
	v_mfma_f32_16x16x32_bf16 v[120:123], v[162:165], v[186:189], v[120:123]
	v_mfma_f32_16x16x32_bf16 v[112:115], v[140:143], v[194:197], v[112:115]
	v_mfma_f32_16x16x32_bf16 v[104:107], v[162:165], v[194:197], v[104:107]
	v_mfma_f32_16x16x32_bf16 v[96:99], v[140:143], v[214:217], v[96:99]
	v_mfma_f32_16x16x32_bf16 v[88:91], v[162:165], v[214:217], v[88:91]
	v_mfma_f32_16x16x32_bf16 v[80:83], v[140:143], v[222:225], v[80:83]
	v_mfma_f32_16x16x32_bf16 v[72:75], v[162:165], v[222:225], v[72:75]
	s_setprio 0
	s_setprio 1
	v_mfma_f32_16x16x32_bf16 v[124:127], v[166:169], v[182:185], v[124:127]
	v_mfma_f32_16x16x32_bf16 v[116:119], v[174:177], v[182:185], v[116:119]
	v_mfma_f32_16x16x32_bf16 v[108:111], v[166:169], v[190:193], v[108:111]
	v_mfma_f32_16x16x32_bf16 v[100:103], v[174:177], v[190:193], v[100:103]
	v_mfma_f32_16x16x32_bf16 v[92:95], v[166:169], v[198:201], v[92:95]
	v_mfma_f32_16x16x32_bf16 v[84:87], v[174:177], v[198:201], v[84:87]
	v_mfma_f32_16x16x32_bf16 v[76:79], v[166:169], v[218:221], v[76:79]
	v_mfma_f32_16x16x32_bf16 v[68:71], v[174:177], v[218:221], v[68:71]
	v_mfma_f32_16x16x32_bf16 v[124:127], v[170:173], v[186:189], v[124:127]
	v_mfma_f32_16x16x32_bf16 v[116:119], v[178:181], v[186:189], v[116:119]
	v_mfma_f32_16x16x32_bf16 v[108:111], v[170:173], v[194:197], v[108:111]
	v_mfma_f32_16x16x32_bf16 v[100:103], v[178:181], v[194:197], v[100:103]
	v_mfma_f32_16x16x32_bf16 v[92:95], v[170:173], v[214:217], v[92:95]
	v_mfma_f32_16x16x32_bf16 v[84:87], v[178:181], v[214:217], v[84:87]
	v_mfma_f32_16x16x32_bf16 v[76:79], v[170:173], v[222:225], v[76:79]
	v_mfma_f32_16x16x32_bf16 v[68:71], v[178:181], v[222:225], v[68:71]
	s_setprio 0
	s_barrier
; __device__ __forceinline__ unsigned pk2(float lo, float hi) { unsigned r; asm("v_cvt_pk_bf16_f32 %0, %1, %2" : "=v"(r) : "v"(lo), "v"(hi)); return r; }
; __device__ __forceinline__ float silu(float x) { return x * sigm(x); }
; #define PG8_STAGE(bufoff, gbase, voff) do { _Pragma("unroll") for (int _i = 0; _i < 2; ++_i) \
;         __builtin_amdgcn_global_load_lds((const unsigned*)((const char*)(gbase) + (voff)[_i]), (LAS unsigned*)(lds + (bufoff) + ldsw + _i * 8192), 16, 0, 0); } while (0)
; #define PG8_LDA(dst, b, h) do { _Pragma("unroll") for (int m = 0; m < 4; ++m) _Pragma("unroll") for (int k = 0; k < 2; ++k) dst[m][k] = *(const LAS bf16x8*)(lds + PG8_SA(b, h) + aoff + m * 2048 + k * 1024); } while (0)
; #define PG8_MMA(ai, bj, At, Bt) do { __builtin_amdgcn_s_setprio(1); _Pragma("unroll") for (int m = 0; m < 4; ++m) _Pragma("unroll") for (int n = 0; n < 2; ++n) _Pragma("unroll") for (int k = 0; k < 2; ++k) \
;         acc[ai][bj][m][n] = __builtin_amdgcn_mfma_f32_16x16x32_bf16(Bt[n][k], At[m][k], acc[ai][bj][m][n], 0, 0, 0); __builtin_amdgcn_s_setprio(0); } while (0)
; #define PG8_WAIT_V(n) asm volatile("s_waitcnt vmcnt(" #n ")" ::: "memory")
;     __device__ __forceinline__ void operator()(const f32x4 (&acc)[2][2][4][2], const Unit& u, int wr, int wc, int fr, int fq) const {
;         const int row0 = u.pm * BM + wr * 64 + fr, col0 = u.pn * HALF + wc * 32 + 8 * fq;
; #pragma unroll
;         for (int ai = 0; ai < 2; ++ai)
; #pragma unroll
;             for (int m = 0; m < 4; ++m) { bf16_t* rowp = O + (size_t)(row0 + ai * HALF + m * 16) * ldc + col0;
;                 const f32x4 g0 = acc[ai][0][m][0], g1 = acc[ai][0][m][1], u0 = acc[ai][1][m][0], u1 = acc[ai][1][m][1];
;                 u32x4 w; w.x = pk2(silu(g0[0]) * u0[0], silu(g0[1]) * u0[1]); w.y = pk2(silu(g0[2]) * u0[2], silu(g0[3]) * u0[3]);
; template <class Epi>
; __device__ __forceinline__ void gemm_phase(LAS unsigned char* lds, const Gemm g, const int G, const int cidx, const Epi& E) {
;     ...
;             PG8_WAIT_V(8); PG8_WAIT_L(0); PG8_BAR; PG8_MMA(0, 0, At, B0); PG8_MMA(0, 1, At, B1); PG8_BAR; PG8_SCHED;
;             PG8_LDA(At, 1, 1); PG8_STAGE(PG8_SB(1, 0), b3, voffB); PG8_STAGE(PG8_SB(1, 1), b3 + hstep, voffB); PG8_STAGE(PG8_SA(1, 0), a3, voffA);
;             PG8_WAIT_V(8); PG8_WAIT_L(0); PG8_BAR; PG8_MMA(1, 0, At, B0); PG8_MMA(1, 1, At, B1); PG8_BAR; PG8_SCHED;
;         }
	s_add_i32 s28, s43, s36
	v_lshl_add_u64 v[226:227], v[226:227], 0, s[46:47]
	s_mov_b32 m0, s28
	ds_read_b128 v[182:185], v161 offset:49152
	ds_read_b128 v[186:189], v161 offset:50176
	ds_read_b128 v[190:193], v161 offset:51200
	ds_read_b128 v[194:197], v161 offset:52224
	ds_read_b128 v[198:201], v161 offset:53248
	ds_read_b128 v[214:217], v161 offset:54272
	ds_read_b128 v[218:221], v161 offset:55296
	ds_read_b128 v[222:225], v161 offset:56320
	global_load_lds_dwordx4 v[226:227], off
	s_add_i32 m0, s28, 0x2000
	s_add_u32 s26, s26, 0x40080
	v_lshl_add_u64 v[226:227], v[228:229], 0, s[46:47]
	s_addc_u32 s27, s27, 0
	s_add_i32 s28, s68, s36
	global_load_lds_dwordx4 v[226:227], off
	v_lshl_add_u64 v[226:227], s[26:27], 0, v[148:149]
	s_mov_b32 m0, s28
	s_nop 0
	global_load_lds_dwordx4 v[226:227], off
	v_lshl_add_u64 v[226:227], s[26:27], 0, v[0:1]
	s_add_i32 m0, s28, 0x2000
	s_nop 0
	global_load_lds_dwordx4 v[226:227], off
	v_lshl_add_u64 v[226:227], v[230:231], 0, s[46:47]
	s_mov_b32 m0, s79
	s_nop 0
	global_load_lds_dwordx4 v[226:227], off
	v_lshl_add_u64 v[226:227], v[232:233], 0, s[46:47]
	s_mov_b32 m0, s34
	s_nop 0
	global_load_lds_dwordx4 v[226:227], off
	s_waitcnt vmcnt(8)
	s_waitcnt lgkmcnt(0)
	s_barrier
	s_setprio 1
	s_waitcnt lgkmcnt(0)
	v_mfma_f32_16x16x32_bf16 v[64:67], v[132:135], v[182:185], v[64:67]
	v_mfma_f32_16x16x32_bf16 v[56:59], v[156:159], v[182:185], v[56:59]
	v_mfma_f32_16x16x32_bf16 v[48:51], v[132:135], v[190:193], v[48:51]
	v_mfma_f32_16x16x32_bf16 v[40:43], v[156:159], v[190:193], v[40:43]
	v_mfma_f32_16x16x32_bf16 v[32:35], v[132:135], v[198:201], v[32:35]
	v_mfma_f32_16x16x32_bf16 v[24:27], v[156:159], v[198:201], v[24:27]
	v_mfma_f32_16x16x32_bf16 v[16:19], v[132:135], v[218:221], v[16:19]
	v_mfma_f32_16x16x32_bf16 v[8:11], v[156:159], v[218:221], v[8:11]
	v_mfma_f32_16x16x32_bf16 v[64:67], v[140:143], v[186:189], v[64:67]
	v_mfma_f32_16x16x32_bf16 v[56:59], v[162:165], v[186:189], v[56:59]
	v_mfma_f32_16x16x32_bf16 v[48:51], v[140:143], v[194:197], v[48:51]
	v_mfma_f32_16x16x32_bf16 v[40:43], v[162:165], v[194:197], v[40:43]
	v_mfma_f32_16x16x32_bf16 v[32:35], v[140:143], v[214:217], v[32:35]
	v_mfma_f32_16x16x32_bf16 v[24:27], v[162:165], v[214:217], v[24:27]
	v_mfma_f32_16x16x32_bf16 v[16:19], v[140:143], v[222:225], v[16:19]
	v_mfma_f32_16x16x32_bf16 v[8:11], v[162:165], v[222:225], v[8:11]
	s_setprio 0
	s_setprio 1
	v_mfma_f32_16x16x32_bf16 v[60:63], v[166:169], v[182:185], v[60:63]
	v_mfma_f32_16x16x32_bf16 v[52:55], v[174:177], v[182:185], v[52:55]
	v_mfma_f32_16x16x32_bf16 v[44:47], v[166:169], v[190:193], v[44:47]
	v_mfma_f32_16x16x32_bf16 v[36:39], v[174:177], v[190:193], v[36:39]
	v_mfma_f32_16x16x32_bf16 v[28:31], v[166:169], v[198:201], v[28:31]
	v_mfma_f32_16x16x32_bf16 v[20:23], v[174:177], v[198:201], v[20:23]
	v_mfma_f32_16x16x32_bf16 v[12:15], v[166:169], v[218:221], v[12:15]
	v_mfma_f32_16x16x32_bf16 v[4:7], v[174:177], v[218:221], v[4:7]
	v_mfma_f32_16x16x32_bf16 v[60:63], v[170:173], v[186:189], v[60:63]
	v_mfma_f32_16x16x32_bf16 v[52:55], v[178:181], v[186:189], v[52:55]
	v_mfma_f32_16x16x32_bf16 v[44:47], v[170:173], v[194:197], v[44:47]
	v_mfma_f32_16x16x32_bf16 v[36:39], v[178:181], v[194:197], v[36:39]
	v_mfma_f32_16x16x32_bf16 v[28:31], v[170:173], v[214:217], v[28:31]
	v_mfma_f32_16x16x32_bf16 v[20:23], v[178:181], v[214:217], v[20:23]
	v_mfma_f32_16x16x32_bf16 v[12:15], v[170:173], v[222:225], v[12:15]
	v_mfma_f32_16x16x32_bf16 v[4:7], v[178:181], v[222:225], v[4:7]
	s_setprio 0
	s_barrier
	s_add_i32 s45, s45, 2
	s_add_u32 s33, s33, 0x100
	s_addc_u32 s44, s44, 0
	s_add_u32 s24, s24, 0x100
	s_addc_u32 s25, s25, 0
	s_cmp_gt_u32 s45, 13
	s_cbranch_scc0 .LBB0_82
	v_lshl_or_b32 v132, s16, 7, v160
	v_lshl_add_u32 v162, s20, 8, v3
	v_ashrrev_i32_e32 v133, 31, v132
	v_mov_b64_e32 v[156:157], s[6:7]
	s_movk_i32 s9, 0x1600
	v_mad_i64_i32 v[134:135], s[16:17], v162, s9, v[156:157]
	v_lshlrev_b64 v[158:159], 1, v[132:133]
	v_lshl_add_u64 v[132:133], v[134:135], 0, v[158:159]
	v_mul_f32_e32 v134, 0xbfb8aa3b, v128
	v_exp_f32_e32 v134, v134
	s_and_b64 vcc, exec, s[4:5]
	s_mov_b32 s20, s12
	s_mov_b64 s[24:25], s[18:19]
	v_add_f32_e32 v134, 1.0, v134
	v_rcp_f32_e32 v134, v134
	s_mov_b64 s[26:27], s[14:15]
	v_mul_f32_e32 v128, v128, v134
	v_mul_f32_e32 v124, v128, v124
	v_mul_f32_e32 v128, 0xbfb8aa3b, v129
	v_exp_f32_e32 v128, v128
	s_nop 0
	v_add_f32_e32 v128, 1.0, v128
	v_rcp_f32_e32 v128, v128
	s_nop 0
	v_mul_f32_e32 v128, v129, v128
	v_mul_f32_e32 v125, v128, v125
	v_cvt_pk_bf16_f32 v124, v124, v125
	v_mul_f32_e32 v125, 0xbfb8aa3b, v130
	v_exp_f32_e32 v125, v125
	s_nop 0
	v_add_f32_e32 v125, 1.0, v125
	v_rcp_f32_e32 v125, v125
	s_nop 0
	v_mul_f32_e32 v125, v130, v125
	v_mul_f32_e32 v125, v125, v126
	v_mul_f32_e32 v126, 0xbfb8aa3b, v131
	v_exp_f32_e32 v126, v126
	s_nop 0
	v_add_f32_e32 v126, 1.0, v126
	v_rcp_f32_e32 v126, v126
	s_nop 0
	v_mul_f32_e32 v126, v131, v126
	v_mul_f32_e32 v126, v126, v127
	v_cvt_pk_bf16_f32 v125, v125, v126
	v_mul_f32_e32 v126, 0xbfb8aa3b, v120
	v_exp_f32_e32 v126, v126
	s_nop 0
	v_add_f32_e32 v126, 1.0, v126
	v_rcp_f32_e32 v126, v126
	s_nop 0
	v_mul_f32_e32 v120, v120, v126
	v_mul_f32_e32 v116, v120, v116
	v_mul_f32_e32 v120, 0xbfb8aa3b, v121
	v_exp_f32_e32 v120, v120
	s_nop 0
	v_add_f32_e32 v120, 1.0, v120
	v_rcp_f32_e32 v120, v120
	s_nop 0
	v_mul_f32_e32 v120, v121, v120
	v_mul_f32_e32 v117, v120, v117
	v_cvt_pk_bf16_f32 v126, v116, v117
	v_mul_f32_e32 v116, 0xbfb8aa3b, v122
	v_exp_f32_e32 v116, v116
	v_mul_f32_e32 v117, 0xbfb8aa3b, v123
	v_exp_f32_e32 v117, v117
	v_add_f32_e32 v116, 1.0, v116
	v_rcp_f32_e32 v116, v116
	v_add_f32_e32 v117, 1.0, v117
	v_rcp_f32_e32 v117, v117
; __device__ __forceinline__ unsigned pk2(float lo, float hi) { unsigned r; asm("v_cvt_pk_bf16_f32 %0, %1, %2" : "=v"(r) : "v"(lo), "v"(hi)); return r; }
; __device__ __forceinline__ float silu(float x) { return x * sigm(x); }
;     __device__ __forceinline__ void operator()(const f32x4 (&acc)[2][2][4][2], const Unit& u, int wr, int wc, int fr, int fq) const {
;     ...
;             for (int m = 0; m < 4; ++m) { bf16_t* rowp = O + (size_t)(row0 + ai * HALF + m * 16) * ldc + col0;
;                 const f32x4 g0 = acc[ai][0][m][0], g1 = acc[ai][0][m][1], u0 = acc[ai][1][m][0], u1 = acc[ai][1][m][1];
;                 u32x4 w; w.x = pk2(silu(g0[0]) * u0[0], silu(g0[1]) * u0[1]); w.y = pk2(silu(g0[2]) * u0[2], silu(g0[3]) * u0[3]);
;                 w.z = pk2(silu(g1[0]) * u1[0], silu(g1[1]) * u1[1]); w.w = pk2(silu(g1[2]) * u1[2], silu(g1[3]) * u1[3]);
;                 *(u32x4*)rowp = w; }
	v_mul_f32_e32 v116, v122, v116
	v_mul_f32_e32 v116, v116, v118
	v_mul_f32_e32 v118, 0xbfb8aa3b, v112
	v_exp_f32_e32 v118, v118
	v_mul_f32_e32 v117, v123, v117
	v_mul_f32_e32 v117, v117, v119
	v_cvt_pk_bf16_f32 v127, v116, v117
	v_add_f32_e32 v118, 1.0, v118
	v_rcp_f32_e32 v118, v118
	s_mov_b64 s[98:99], 0x16000
	v_mul_f32_e32 v112, v112, v118
	v_mul_f32_e32 v108, v112, v108
	v_mul_f32_e32 v112, 0xbfb8aa3b, v113
	v_exp_f32_e32 v112, v112
	v_lshl_add_u64 v[116:117], v[132:133], 0, s[98:99]
	global_store_dwordx4 v[132:133], v[124:127], off
	v_add_f32_e32 v112, 1.0, v112
	v_rcp_f32_e32 v112, v112
	s_nop 0
	v_mul_f32_e32 v112, v113, v112
	v_mul_f32_e32 v109, v112, v109
	v_cvt_pk_bf16_f32 v108, v108, v109
	v_mul_f32_e32 v109, 0xbfb8aa3b, v114
	v_exp_f32_e32 v109, v109
	s_nop 0
	v_add_f32_e32 v109, 1.0, v109
	v_rcp_f32_e32 v109, v109
	s_nop 0
	v_mul_f32_e32 v109, v114, v109
	v_mul_f32_e32 v109, v109, v110
	v_mul_f32_e32 v110, 0xbfb8aa3b, v115
	v_exp_f32_e32 v110, v110
	s_nop 0
	v_add_f32_e32 v110, 1.0, v110
	v_rcp_f32_e32 v110, v110
	s_nop 0
	v_mul_f32_e32 v110, v115, v110
	v_mul_f32_e32 v110, v110, v111
	v_cvt_pk_bf16_f32 v109, v109, v110
	v_mul_f32_e32 v110, 0xbfb8aa3b, v104
	v_exp_f32_e32 v110, v110
	s_nop 0
	v_add_f32_e32 v110, 1.0, v110
	v_rcp_f32_e32 v110, v110
	s_nop 0
	v_mul_f32_e32 v104, v104, v110
	v_mul_f32_e32 v100, v104, v100
	v_mul_f32_e32 v104, 0xbfb8aa3b, v105
	v_exp_f32_e32 v104, v104
	s_nop 0
	v_add_f32_e32 v104, 1.0, v104
	v_rcp_f32_e32 v104, v104
	s_nop 0
	v_mul_f32_e32 v104, v105, v104
	v_mul_f32_e32 v101, v104, v101
	v_cvt_pk_bf16_f32 v110, v100, v101
	v_mul_f32_e32 v100, 0xbfb8aa3b, v106
	v_exp_f32_e32 v100, v100
	v_mul_f32_e32 v101, 0xbfb8aa3b, v107
	v_exp_f32_e32 v101, v101
	v_add_f32_e32 v100, 1.0, v100
	v_rcp_f32_e32 v100, v100
	v_add_f32_e32 v101, 1.0, v101
	v_rcp_f32_e32 v101, v101
	v_mul_f32_e32 v100, v106, v100
	v_mul_f32_e32 v100, v100, v102
	v_mul_f32_e32 v102, 0xbfb8aa3b, v96
	v_exp_f32_e32 v102, v102
	v_mul_f32_e32 v101, v107, v101
	v_mul_f32_e32 v101, v101, v103
	v_cvt_pk_bf16_f32 v111, v100, v101
	v_add_f32_e32 v102, 1.0, v102
	v_rcp_f32_e32 v102, v102
	s_mov_b64 s[98:99], 0x2c000
	v_mul_f32_e32 v96, v96, v102
	v_mul_f32_e32 v92, v96, v92
	v_mul_f32_e32 v96, 0xbfb8aa3b, v97
	v_exp_f32_e32 v96, v96
	v_lshl_add_u64 v[100:101], v[132:133], 0, s[98:99]
	global_store_dwordx4 v[116:117], v[108:111], off
	v_add_f32_e32 v96, 1.0, v96
	v_rcp_f32_e32 v96, v96
	s_nop 0
	v_mul_f32_e32 v96, v97, v96
	v_mul_f32_e32 v93, v96, v93
	v_cvt_pk_bf16_f32 v92, v92, v93
	v_mul_f32_e32 v93, 0xbfb8aa3b, v98
	v_exp_f32_e32 v93, v93
	s_nop 0
	v_add_f32_e32 v93, 1.0, v93
	v_rcp_f32_e32 v93, v93
	s_nop 0
	v_mul_f32_e32 v93, v98, v93
	v_mul_f32_e32 v93, v93, v94
	v_mul_f32_e32 v94, 0xbfb8aa3b, v99
	v_exp_f32_e32 v94, v94
	s_nop 0
	v_add_f32_e32 v94, 1.0, v94
	v_rcp_f32_e32 v94, v94
	s_nop 0
	v_mul_f32_e32 v94, v99, v94
	v_mul_f32_e32 v94, v94, v95
	v_cvt_pk_bf16_f32 v93, v93, v94
	v_mul_f32_e32 v94, 0xbfb8aa3b, v88
	v_exp_f32_e32 v94, v94
	s_nop 0
	v_add_f32_e32 v94, 1.0, v94
	v_rcp_f32_e32 v94, v94
	s_nop 0
	v_mul_f32_e32 v88, v88, v94
	v_mul_f32_e32 v84, v88, v84
	v_mul_f32_e32 v88, 0xbfb8aa3b, v89
	v_exp_f32_e32 v88, v88
	s_nop 0
	v_add_f32_e32 v88, 1.0, v88
	v_rcp_f32_e32 v88, v88
	s_nop 0
	v_mul_f32_e32 v88, v89, v88
	v_mul_f32_e32 v85, v88, v85
	v_cvt_pk_bf16_f32 v94, v84, v85
	v_mul_f32_e32 v84, 0xbfb8aa3b, v90
	v_exp_f32_e32 v84, v84
	v_mul_f32_e32 v85, 0xbfb8aa3b, v91
	v_exp_f32_e32 v85, v85
	v_add_f32_e32 v84, 1.0, v84
	v_rcp_f32_e32 v84, v84
	v_add_f32_e32 v85, 1.0, v85
	v_rcp_f32_e32 v85, v85
	v_mul_f32_e32 v84, v90, v84
	v_mul_f32_e32 v84, v84, v86
	v_mul_f32_e32 v86, 0xbfb8aa3b, v80
	v_exp_f32_e32 v86, v86
	v_mul_f32_e32 v85, v91, v85
	v_mul_f32_e32 v85, v85, v87
	v_cvt_pk_bf16_f32 v95, v84, v85
	v_add_f32_e32 v86, 1.0, v86
	v_rcp_f32_e32 v86, v86
	s_mov_b64 s[98:99], 0x42000
	v_mul_f32_e32 v80, v80, v86
	v_mul_f32_e32 v76, v80, v76
	v_mul_f32_e32 v80, 0xbfb8aa3b, v81
	v_exp_f32_e32 v80, v80
	v_lshl_add_u64 v[84:85], v[132:133], 0, s[98:99]
	global_store_dwordx4 v[100:101], v[92:95], off
	v_add_f32_e32 v80, 1.0, v80
	v_rcp_f32_e32 v80, v80
	s_nop 0
	v_mul_f32_e32 v80, v81, v80
	v_mul_f32_e32 v77, v80, v77
	v_cvt_pk_bf16_f32 v76, v76, v77
	v_mul_f32_e32 v77, 0xbfb8aa3b, v82
	v_exp_f32_e32 v77, v77
	s_nop 0
	v_add_f32_e32 v77, 1.0, v77
	v_rcp_f32_e32 v77, v77
	s_nop 0
	v_mul_f32_e32 v77, v82, v77
	v_mul_f32_e32 v77, v77, v78
	v_mul_f32_e32 v78, 0xbfb8aa3b, v83
	v_exp_f32_e32 v78, v78
	s_nop 0
	v_add_f32_e32 v78, 1.0, v78
	v_rcp_f32_e32 v78, v78
	s_nop 0
	v_mul_f32_e32 v78, v83, v78
	v_mul_f32_e32 v78, v78, v79
	v_cvt_pk_bf16_f32 v77, v77, v78
	v_mul_f32_e32 v78, 0xbfb8aa3b, v72
	v_exp_f32_e32 v78, v78
	s_nop 0
	v_add_f32_e32 v78, 1.0, v78
	v_rcp_f32_e32 v78, v78
	s_nop 0
	v_mul_f32_e32 v72, v72, v78
	v_mul_f32_e32 v68, v72, v68
	v_mul_f32_e32 v72, 0xbfb8aa3b, v73
	v_exp_f32_e32 v72, v72
	s_nop 0
	v_add_f32_e32 v72, 1.0, v72
	v_rcp_f32_e32 v72, v72
	s_nop 0
	v_mul_f32_e32 v72, v73, v72
	v_mul_f32_e32 v69, v72, v69
	v_cvt_pk_bf16_f32 v78, v68, v69
	v_mul_f32_e32 v68, 0xbfb8aa3b, v74
	v_exp_f32_e32 v68, v68
	v_mul_f32_e32 v69, 0xbfb8aa3b, v75
	v_exp_f32_e32 v69, v69
	v_add_f32_e32 v68, 1.0, v68
	v_rcp_f32_e32 v68, v68
	v_add_f32_e32 v69, 1.0, v69
	v_rcp_f32_e32 v69, v69
	v_mul_f32_e32 v68, v74, v68
	v_mul_f32_e32 v68, v68, v70
	v_mul_f32_e32 v70, 0xbfb8aa3b, v64
	v_exp_f32_e32 v70, v70
	v_mul_f32_e32 v69, v75, v69
	v_mul_f32_e32 v69, v69, v71
	v_cvt_pk_bf16_f32 v79, v68, v69
	v_add_f32_e32 v70, 1.0, v70
	v_rcp_f32_e32 v70, v70
	s_mov_b64 s[98:99], 0xb0000
	v_mul_f32_e32 v64, v64, v70
	v_mul_f32_e32 v60, v64, v60
; __device__ __forceinline__ unsigned pk2(float lo, float hi) { unsigned r; asm("v_cvt_pk_bf16_f32 %0, %1, %2" : "=v"(r) : "v"(lo), "v"(hi)); return r; }
; __device__ __forceinline__ float silu(float x) { return x * sigm(x); }
;     __device__ __forceinline__ void operator()(const f32x4 (&acc)[2][2][4][2], const Unit& u, int wr, int wc, int fr, int fq) const {
;     ...
;             for (int m = 0; m < 4; ++m) { bf16_t* rowp = O + (size_t)(row0 + ai * HALF + m * 16) * ldc + col0;
;                 const f32x4 g0 = acc[ai][0][m][0], g1 = acc[ai][0][m][1], u0 = acc[ai][1][m][0], u1 = acc[ai][1][m][1];
;                 u32x4 w; w.x = pk2(silu(g0[0]) * u0[0], silu(g0[1]) * u0[1]); w.y = pk2(silu(g0[2]) * u0[2], silu(g0[3]) * u0[3]);
;                 w.z = pk2(silu(g1[0]) * u1[0], silu(g1[1]) * u1[1]); w.w = pk2(silu(g1[2]) * u1[2], silu(g1[3]) * u1[3]);
;                 *(u32x4*)rowp = w; }
	v_mul_f32_e32 v64, 0xbfb8aa3b, v65
	v_exp_f32_e32 v64, v64
	v_lshl_add_u64 v[68:69], v[132:133], 0, s[98:99]
	global_store_dwordx4 v[84:85], v[76:79], off
	v_add_f32_e32 v64, 1.0, v64
	v_rcp_f32_e32 v64, v64
	s_nop 0
	v_mul_f32_e32 v64, v65, v64
	v_mul_f32_e32 v61, v64, v61
	v_cvt_pk_bf16_f32 v60, v60, v61
	v_mul_f32_e32 v61, 0xbfb8aa3b, v66
	v_exp_f32_e32 v61, v61
	s_nop 0
	v_add_f32_e32 v61, 1.0, v61
	v_rcp_f32_e32 v61, v61
	s_nop 0
	v_mul_f32_e32 v61, v66, v61
	v_mul_f32_e32 v61, v61, v62
	v_mul_f32_e32 v62, 0xbfb8aa3b, v67
	v_exp_f32_e32 v62, v62
	s_nop 0
	v_add_f32_e32 v62, 1.0, v62
	v_rcp_f32_e32 v62, v62
	s_nop 0
	v_mul_f32_e32 v62, v67, v62
	v_mul_f32_e32 v62, v62, v63
	v_cvt_pk_bf16_f32 v61, v61, v62
	v_mul_f32_e32 v62, 0xbfb8aa3b, v56
	v_exp_f32_e32 v62, v62
	s_nop 0
	v_add_f32_e32 v62, 1.0, v62
	v_rcp_f32_e32 v62, v62
	s_nop 0
	v_mul_f32_e32 v56, v56, v62
	v_mul_f32_e32 v52, v56, v52
	v_mul_f32_e32 v56, 0xbfb8aa3b, v57
	v_exp_f32_e32 v56, v56
	s_nop 0
	v_add_f32_e32 v56, 1.0, v56
	v_rcp_f32_e32 v56, v56
	s_nop 0
	v_mul_f32_e32 v56, v57, v56
	v_mul_f32_e32 v53, v56, v53
	v_cvt_pk_bf16_f32 v62, v52, v53
	v_mul_f32_e32 v52, 0xbfb8aa3b, v58
	v_exp_f32_e32 v52, v52
	v_mul_f32_e32 v53, 0xbfb8aa3b, v59
	v_exp_f32_e32 v53, v53
	v_add_f32_e32 v52, 1.0, v52
	v_rcp_f32_e32 v52, v52
	v_add_f32_e32 v53, 1.0, v53
	v_rcp_f32_e32 v53, v53
	v_mul_f32_e32 v52, v58, v52
	v_mul_f32_e32 v52, v52, v54
	v_mul_f32_e32 v54, 0xbfb8aa3b, v48
	v_exp_f32_e32 v54, v54
	v_mul_f32_e32 v53, v59, v53
	v_mul_f32_e32 v53, v53, v55
	v_cvt_pk_bf16_f32 v63, v52, v53
	v_add_f32_e32 v54, 1.0, v54
	v_rcp_f32_e32 v54, v54
	s_mov_b64 s[98:99], 0xc6000
	v_mul_f32_e32 v48, v48, v54
	v_mul_f32_e32 v44, v48, v44
	v_mul_f32_e32 v48, 0xbfb8aa3b, v49
	v_exp_f32_e32 v48, v48
	v_lshl_add_u64 v[52:53], v[132:133], 0, s[98:99]
	global_store_dwordx4 v[68:69], v[60:63], off
	v_add_f32_e32 v48, 1.0, v48
	v_rcp_f32_e32 v48, v48
	s_nop 0
	v_mul_f32_e32 v48, v49, v48
	v_mul_f32_e32 v45, v48, v45
	v_cvt_pk_bf16_f32 v44, v44, v45
	v_mul_f32_e32 v45, 0xbfb8aa3b, v50
	v_exp_f32_e32 v45, v45
	s_nop 0
	v_add_f32_e32 v45, 1.0, v45
	v_rcp_f32_e32 v45, v45
	s_nop 0
	v_mul_f32_e32 v45, v50, v45
	v_mul_f32_e32 v45, v45, v46
	v_mul_f32_e32 v46, 0xbfb8aa3b, v51
	v_exp_f32_e32 v46, v46
	s_nop 0
	v_add_f32_e32 v46, 1.0, v46
	v_rcp_f32_e32 v46, v46
	s_nop 0
	v_mul_f32_e32 v46, v51, v46
	v_mul_f32_e32 v46, v46, v47
	v_cvt_pk_bf16_f32 v45, v45, v46
	v_mul_f32_e32 v46, 0xbfb8aa3b, v40
	v_exp_f32_e32 v46, v46
	s_nop 0
	v_add_f32_e32 v46, 1.0, v46
	v_rcp_f32_e32 v46, v46
	s_nop 0
	v_mul_f32_e32 v40, v40, v46
	v_mul_f32_e32 v36, v40, v36
	v_mul_f32_e32 v40, 0xbfb8aa3b, v41
	v_exp_f32_e32 v40, v40
	s_nop 0
	v_add_f32_e32 v40, 1.0, v40
	v_rcp_f32_e32 v40, v40
	s_nop 0
	v_mul_f32_e32 v40, v41, v40
	v_mul_f32_e32 v37, v40, v37
	v_cvt_pk_bf16_f32 v46, v36, v37
	v_mul_f32_e32 v36, 0xbfb8aa3b, v42
	v_exp_f32_e32 v36, v36
	v_mul_f32_e32 v37, 0xbfb8aa3b, v43
	v_exp_f32_e32 v37, v37
	v_add_f32_e32 v36, 1.0, v36
	v_rcp_f32_e32 v36, v36
	v_add_f32_e32 v37, 1.0, v37
	v_rcp_f32_e32 v37, v37
	v_mul_f32_e32 v36, v42, v36
	v_mul_f32_e32 v36, v36, v38
	v_mul_f32_e32 v38, 0xbfb8aa3b, v32
	v_exp_f32_e32 v38, v38
	v_mul_f32_e32 v37, v43, v37
	v_mul_f32_e32 v37, v37, v39
	v_cvt_pk_bf16_f32 v47, v36, v37
	v_add_f32_e32 v38, 1.0, v38
	v_rcp_f32_e32 v38, v38
	s_mov_b64 s[98:99], 0xdc000
	v_mul_f32_e32 v32, v32, v38
	v_mul_f32_e32 v28, v32, v28
	v_mul_f32_e32 v32, 0xbfb8aa3b, v33
	v_exp_f32_e32 v32, v32
	v_lshl_add_u64 v[36:37], v[132:133], 0, s[98:99]
	global_store_dwordx4 v[52:53], v[44:47], off
	v_add_f32_e32 v32, 1.0, v32
	v_rcp_f32_e32 v32, v32
	s_nop 0
	v_mul_f32_e32 v32, v33, v32
	v_mul_f32_e32 v29, v32, v29
	v_cvt_pk_bf16_f32 v28, v28, v29
	v_mul_f32_e32 v29, 0xbfb8aa3b, v34
	v_exp_f32_e32 v29, v29
	s_nop 0
	v_add_f32_e32 v29, 1.0, v29
	v_rcp_f32_e32 v29, v29
	s_nop 0
	v_mul_f32_e32 v29, v34, v29
	v_mul_f32_e32 v29, v29, v30
	v_mul_f32_e32 v30, 0xbfb8aa3b, v35
	v_exp_f32_e32 v30, v30
	s_nop 0
	v_add_f32_e32 v30, 1.0, v30
	v_rcp_f32_e32 v30, v30
	s_nop 0
	v_mul_f32_e32 v30, v35, v30
	v_mul_f32_e32 v30, v30, v31
	v_cvt_pk_bf16_f32 v29, v29, v30
	v_mul_f32_e32 v30, 0xbfb8aa3b, v24
	v_exp_f32_e32 v30, v30
	s_nop 0
	v_add_f32_e32 v30, 1.0, v30
	v_rcp_f32_e32 v30, v30
	s_nop 0
	v_mul_f32_e32 v24, v24, v30
	v_mul_f32_e32 v20, v24, v20
	v_mul_f32_e32 v24, 0xbfb8aa3b, v25
	v_exp_f32_e32 v24, v24
	s_nop 0
	v_add_f32_e32 v24, 1.0, v24
	v_rcp_f32_e32 v24, v24
	s_nop 0
	v_mul_f32_e32 v24, v25, v24
	v_mul_f32_e32 v21, v24, v21
	v_cvt_pk_bf16_f32 v30, v20, v21
	v_mul_f32_e32 v20, 0xbfb8aa3b, v26
	v_exp_f32_e32 v20, v20
	v_mul_f32_e32 v21, 0xbfb8aa3b, v27
	v_exp_f32_e32 v21, v21
	v_add_f32_e32 v20, 1.0, v20
	v_rcp_f32_e32 v20, v20
	v_add_f32_e32 v21, 1.0, v21
	v_rcp_f32_e32 v21, v21
	v_mul_f32_e32 v20, v26, v20
	v_mul_f32_e32 v20, v20, v22
	v_mul_f32_e32 v22, 0xbfb8aa3b, v16
	v_exp_f32_e32 v22, v22
	v_mul_f32_e32 v21, v27, v21
	v_mul_f32_e32 v21, v21, v23
	v_cvt_pk_bf16_f32 v31, v20, v21
	v_add_f32_e32 v22, 1.0, v22
	v_rcp_f32_e32 v22, v22
	s_mov_b64 s[98:99], 0xf2000
	v_mul_f32_e32 v16, v16, v22
	v_mul_f32_e32 v12, v16, v12
	v_mul_f32_e32 v16, 0xbfb8aa3b, v17
	v_exp_f32_e32 v16, v16
	v_lshl_add_u64 v[20:21], v[132:133], 0, s[98:99]
	s_mov_b32 s16, s8
	global_store_dwordx4 v[36:37], v[28:31], off
	v_add_f32_e32 v16, 1.0, v16
	v_rcp_f32_e32 v16, v16
	s_nop 0
	v_mul_f32_e32 v16, v17, v16
	v_mul_f32_e32 v13, v16, v13
	v_cvt_pk_bf16_f32 v12, v12, v13
	v_mul_f32_e32 v13, 0xbfb8aa3b, v18
	v_exp_f32_e32 v13, v13
	s_nop 0
	v_add_f32_e32 v13, 1.0, v13
	v_rcp_f32_e32 v13, v13
	s_nop 0
	v_mul_f32_e32 v13, v18, v13
	v_mul_f32_e32 v13, v13, v14
	v_mul_f32_e32 v14, 0xbfb8aa3b, v19
	v_exp_f32_e32 v14, v14
	s_nop 0
	v_add_f32_e32 v14, 1.0, v14
	v_rcp_f32_e32 v14, v14
	s_nop 0
	v_mul_f32_e32 v14, v19, v14
	v_mul_f32_e32 v14, v14, v15
	v_cvt_pk_bf16_f32 v13, v13, v14
	v_mul_f32_e32 v14, 0xbfb8aa3b, v8
	v_exp_f32_e32 v14, v14
	s_nop 0
	v_add_f32_e32 v14, 1.0, v14
	v_rcp_f32_e32 v14, v14
	s_nop 0
	v_mul_f32_e32 v8, v8, v14
	v_mul_f32_e32 v4, v8, v4
	v_mul_f32_e32 v8, 0xbfb8aa3b, v9
	v_exp_f32_e32 v8, v8
	s_nop 0
	v_add_f32_e32 v8, 1.0, v8
	v_rcp_f32_e32 v8, v8
	s_nop 0
	v_mul_f32_e32 v8, v9, v8
	v_mul_f32_e32 v5, v8, v5
	v_cvt_pk_bf16_f32 v14, v4, v5
	v_mul_f32_e32 v4, 0xbfb8aa3b, v10
	v_mul_f32_e32 v5, 0xbfb8aa3b, v11
	v_exp_f32_e32 v4, v4
	v_exp_f32_e32 v5, v5
	v_add_f32_e32 v4, 1.0, v4
	v_add_f32_e32 v5, 1.0, v5
	v_rcp_f32_e32 v4, v4
	v_rcp_f32_e32 v5, v5
	v_mul_f32_e32 v4, v10, v4
	v_mul_f32_e32 v5, v11, v5
	v_mul_f32_e32 v4, v4, v6
	v_mul_f32_e32 v5, v5, v7
	v_cvt_pk_bf16_f32 v15, v4, v5
	global_store_dwordx4 v[20:21], v[12:15], off
	s_cbranch_vccz .LBB0_79
	s_waitcnt vmcnt(0)
	s_cmpk_gt_u32 s95, 0xff
	s_mov_b32 s73, s83
	v_readlane_b32 s79, v255, 21
	s_cbranch_scc1 .LBB0_86
	s_barrier
